# prompt attention: post-loop drain of the trailing re-load DMAs moved from before the last tile to the barrier that frees LDS for the epilogue (on top of the prologue over-drain removal)
# baseline (speedup 1.0000x reference)
; #define SBAR() __builtin_amdgcn_sched_barrier(0)
; #define FIN(P0, P1) do { PK4(P0, 0, pa0); PK4(P0, 8, pa1); PK4(P1, 0, pa2); PK4(P1, 8, pa3); } while (0)
; __device__ __forceinline__ void attn_prompt(Frame& F, int b, int h, int qb, float lam, float mshift) {
;     ...
;     asm volatile("s_waitcnt vmcnt(0)" ::: "memory");
;     SBAR(); if (vis) { QKT(pB0, pB1, s_cur, NT - 1); } FIN(pA0, pA1); SBAR();
.LBB0_517:
	s_nop 0
	s_cmp_lg_u32 s83, s2
	s_cselect_b64 s[0:1], -1, 0
	s_cmp_eq_u32 s83, s2
	s_cbranch_scc0 .LBB0_519
	s_lshl_b32 s2, s2, 6
	v_sub_u32_e32 v90, s2, v201
	s_add_i32 s3, s65, 0
	v_lshlrev_b32_e32 v90, 2, v90
	s_add_i32 s2, 0, 0x20400
	v_add_u32_e32 v86, s3, v200
	v_add3_u32 v90, s2, v90, v194
	ds_read_b128 v[82:85], v86
	ds_read_b128 v[86:89], v86 offset:8192
	ds_read2_b32 v[114:115], v90 offset0:191 offset1:192
	ds_read2_b32 v[116:117], v90 offset0:193 offset1:194
	ds_read2_b32 v[118:119], v90 offset0:199 offset1:200
	ds_read2_b32 v[120:121], v90 offset0:201 offset1:202
	ds_read2_b32 v[122:123], v90 offset0:207 offset1:208
	ds_read2_b32 v[124:125], v90 offset0:209 offset1:210
	ds_read2_b32 v[126:127], v90 offset0:215 offset1:216
	ds_read2_b32 v[128:129], v90 offset0:217 offset1:218
	ds_read2_b32 v[98:99], v90 offset0:223 offset1:224
	ds_read2_b32 v[100:101], v90 offset0:225 offset1:226
	ds_read2_b32 v[102:103], v90 offset0:231 offset1:232
	ds_read2_b32 v[104:105], v90 offset0:233 offset1:234
	ds_read2_b32 v[106:107], v90 offset0:239 offset1:240
	ds_read2_b32 v[108:109], v90 offset0:241 offset1:242
	ds_read2_b32 v[110:111], v90 offset0:247 offset1:248
	ds_read2_b32 v[112:113], v90 offset0:249 offset1:250
	s_waitcnt lgkmcnt(8)
	v_mfma_f32_32x32x16_bf16 v[114:129], v[82:85], v[174:177], v[114:129]
	v_add_u32_e32 v90, s3, v195
	s_waitcnt lgkmcnt(0)
	v_mfma_f32_32x32x16_bf16 v[98:113], v[86:89], v[174:177], v[98:113]
	v_add_u32_e32 v86, v90, v202
	ds_read_b128 v[82:85], v86
	ds_read_b128 v[86:89], v86 offset:8192
	s_waitcnt lgkmcnt(1)
	v_mfma_f32_32x32x16_bf16 v[114:129], v[82:85], v[170:173], v[114:129]
	s_waitcnt lgkmcnt(0)
	v_mfma_f32_32x32x16_bf16 v[98:113], v[86:89], v[170:173], v[98:113]
	v_add_u32_e32 v86, v90, v203
	ds_read_b128 v[82:85], v86
	ds_read_b128 v[86:89], v86 offset:8192
	s_waitcnt lgkmcnt(1)
	v_mfma_f32_32x32x16_bf16 v[114:129], v[82:85], v[166:169], v[114:129]
	s_waitcnt lgkmcnt(0)
	v_mfma_f32_32x32x16_bf16 v[98:113], v[86:89], v[166:169], v[98:113]
	v_add_u32_e32 v86, v90, v204
	ds_read_b128 v[82:85], v86
	ds_read_b128 v[86:89], v86 offset:8192
	s_waitcnt lgkmcnt(1)
	v_mfma_f32_32x32x16_bf16 v[114:129], v[82:85], v[162:165], v[114:129]
	s_waitcnt lgkmcnt(0)
	v_mfma_f32_32x32x16_bf16 v[98:113], v[86:89], v[162:165], v[98:113]

; #define PTS_BEGIN(id, cond) do { if (PROBE_TS == (id) && blockIdx.x == 0 && (cond)) F.pt0 = __builtin_amdgcn_s_memrealtime(); } while (0)
; #define PTS_END(id, cond) do { if (PROBE_TS == (id) && blockIdx.x == 0 && (cond)) F.pacc += __builtin_amdgcn_s_memrealtime() - F.pt0; } while (0)
; #define GAS __attribute__((address_space(1)))
; #define LAS __attribute__((address_space(3)))
; __device__ __forceinline__ void attn_prompt(Frame& F, int b, int h, int qb, float lam, float mshift) {
;     ...
;     __syncthreads();
;     PTS_END(1, qb == 15 && F.pt0 != 0 && F.pacc == 0); PTS_BEGIN(2, qb == 15 && F.pacc == 0);
;     LAS float* X = (LAS float*)L;
;     int tid2 = tid; asm volatile("" : "+v"(tid2));
;     const int erow = tid2 >> 3, eoc = tid2 & 7;
;     v4u zz[4]; f32x4 gg[4];
;     { const bf16* zp = ZB + (qrow0 + erow) * DM + h * 128 + 8 * eoc; const float* gp = F.in[22] + 8 * eoc;
; #pragma unroll
;       for (int i = 0; i < 4; ++i) zz[i] = *(const GAS v4u*)(zp + (size_t)(i >> 1) * 64 * DM + 64 * (i & 1));
; #pragma unroll
;       for (int i = 0; i < 4; ++i) gg[i] = *(const GAS f32x4*)(gp + 64 * (i >> 1) + 4 * (i & 1)); }
;     float fr_[16];
;     { const float fm = (m == 0 ? 1.f : __builtin_bit_cast(float, F.MISC[16]));
; #pragma unroll
;       for (int r = 0; r < 16; ++r) fr_[r] = fm * __builtin_amdgcn_rcpf(ol[r]); }
.LBB0_523:
	s_waitcnt vmcnt(0)
	s_barrier
	s_mov_b32 s55, s11
	v_ashrrev_i32_e32 v34, 3, v219
	v_ashrrev_i32_e32 v35, 31, v34
	v_lshl_add_u64 v[36:37], s[52:53], 0, v[34:35]
	v_lshlrev_b64 v[2:3], 11, v[36:37]
	v_lshlrev_b32_e32 v4, 3, v219
	v_lshl_add_u64 v[2:3], s[26:27], 0, v[2:3]
	v_and_b32_e32 v6, 56, v4
	v_lshl_add_u64 v[2:3], v[2:3], 0, s[54:55]
	v_lshlrev_b32_e32 v210, 1, v6
	v_lshl_add_u64 v[2:3], v[2:3], 0, v[210:211]
	global_load_dwordx4 v[30:33], v[2:3], off
	global_load_dwordx4 v[26:29], v[2:3], off offset:128
	v_add_co_u32_e32 v2, vcc, 0x20000, v2
	v_lshlrev_b32_e32 v35, 2, v6
	s_nop 0
	v_addc_co_u32_e32 v3, vcc, 0, v3, vcc
	global_load_dwordx4 v[14:17], v[2:3], off
	s_nop 0
	global_load_dwordx4 v[2:5], v[2:3], off offset:128
	s_nop 0
	global_load_dwordx4 v[18:21], v35, s[48:49] offset:16
	global_load_dwordx4 v[22:25], v35, s[48:49]
	global_load_dwordx4 v[6:9], v35, s[48:49] offset:272
	global_load_dwordx4 v[10:13], v35, s[48:49] offset:256
	s_andn2_b64 vcc, exec, s[40:41]
	v_mov_b32_e32 v52, 1.0
	s_cbranch_vccnz .LBB0_525
	v_readlane_b32 s0, v255, 18
	s_nop 1
	v_mov_b32_e32 v38, s0
	ds_read_b32 v52, v38
